# attention: one LDS wait per group of four MFMAs instead of one per MFMA
# baseline (speedup 1.0000x reference)
; __device__ __forceinline__ unsigned cvt_pk_bf16(float lo, float hi) { unsigned r; asm volatile("v_cvt_pk_bf16_f32 %0, %1, %2" : "=v"(r) : "v"(lo), "v"(hi)); return r; }
; __device__ __forceinline__ void phase_attn(const Params& p, unsigned char* lds) {
;     ...
;             AT_QK(st, buf);
;             float mloc = st[0][0];
; #pragma unroll
;             for (int i = 0; i < 16; ++i) { mloc = fmaxf(mloc, st[0][i]); mloc = fmaxf(mloc, st[1][i]); }
;             mloc = fmaxf(mloc, __shfl_xor(mloc, 32));
;             const float mnew = fmaxf(mrun, mloc);
;             if (__builtin_amdgcn_ballot_w64(mnew > mrun) != 0ull) {
;                 const float alpha = __builtin_amdgcn_exp2f(mrun - mnew);
;                 lsum *= alpha;
; #pragma unroll
;                 for (int vb = 0; vb < 4; ++vb)
; #pragma unroll
;                     for (int i = 0; i < 16; ++i) ot[vb][i] *= alpha;
;             }
;             mrun = mnew;
;             bf16x8 P[2][2];
; #pragma unroll
;             for (int kb = 0; kb < 2; ++kb)
; #pragma unroll
;                 for (int s2 = 0; s2 < 2; ++s2) { u32x4 pk;
; #pragma unroll
;                     for (int jj = 0; jj < 4; ++jj) { const float p0 = __builtin_amdgcn_exp2f(st[kb][8 * s2 + 2 * jj] - mnew), p1 = __builtin_amdgcn_exp2f(st[kb][8 * s2 + 2 * jj + 1] - mnew); lsum += p0 + p1; pk[jj] = cvt_pk_bf16(p0, p1); }
;                     P[kb][s2] = __builtin_bit_cast(bf16x8, pk); }
;             {
;                 bf16x8 vf[2][4];
;     ...
;                 AT_LDV(0, 0);
; #pragma unroll
;                 for (int vb = 0; vb < 4; ++vb) {
;                     if (vb < 3) AT_LDV((vb + 1) & 1, vb + 1);
;                     __builtin_amdgcn_sched_barrier(0);
;                     __builtin_amdgcn_s_setprio(2);
; #pragma unroll
;                     for (int kb = 0; kb < 2; ++kb)
; #pragma unroll
;                         for (int s2 = 0; s2 < 2; ++s2) ot[vb] = __builtin_amdgcn_mfma_f32_32x32x16_bf16(vf[vb & 1][kb * 2 + s2], P[kb][s2], ot[vb], 0, 0, 0);
;                     __builtin_amdgcn_s_setprio(0);
;                     __builtin_amdgcn_sched_barrier(0);
;                 }
;     ...
;             }
;             if (kt + 1 < 64) { AT_STOREK(buf ^ 1); AT_STOREV(buf ^ 1); }
.Lat_norescale_1:
	v_mov_b32_e32 v236, 0
	s_waitcnt lgkmcnt(4)
	v_mfma_f32_32x32x16_bf16 v[196:211], v[172:175], v[108:111], 0
	v_sub_f32_e32 v80, v80, v149
	v_sub_f32_e32 v81, v81, v149
	v_exp_f32_e32 v80, v80
	v_exp_f32_e32 v81, v81
	v_add_f32_e32 v128, v128, v80
	v_add_f32_e32 v236, v236, v81
	v_cvt_pk_bf16_f32 v80, v80, v81
	v_sub_f32_e32 v82, v82, v149
	v_sub_f32_e32 v83, v83, v149
	v_exp_f32_e32 v82, v82
	v_exp_f32_e32 v83, v83
	v_add_f32_e32 v128, v128, v82
	v_add_f32_e32 v236, v236, v83
	v_cvt_pk_bf16_f32 v81, v82, v83
	v_mfma_f32_32x32x16_bf16 v[196:211], v[176:179], v[104:107], v[196:211]
	v_sub_f32_e32 v84, v84, v149
	v_sub_f32_e32 v85, v85, v149
	v_exp_f32_e32 v84, v84
	v_exp_f32_e32 v85, v85
	v_add_f32_e32 v128, v128, v84
	v_add_f32_e32 v236, v236, v85
	v_cvt_pk_bf16_f32 v82, v84, v85
	v_sub_f32_e32 v86, v86, v149
	v_sub_f32_e32 v87, v87, v149
	v_exp_f32_e32 v86, v86
	v_exp_f32_e32 v87, v87
	v_add_f32_e32 v128, v128, v86
	v_add_f32_e32 v236, v236, v87
	v_cvt_pk_bf16_f32 v83, v86, v87
	v_mfma_f32_32x32x16_bf16 v[196:211], v[180:183], v[100:103], v[196:211]
	v_sub_f32_e32 v88, v88, v149
	v_sub_f32_e32 v89, v89, v149
	v_exp_f32_e32 v88, v88
	v_exp_f32_e32 v89, v89
	v_add_f32_e32 v128, v128, v88
	v_add_f32_e32 v236, v236, v89
	v_cvt_pk_bf16_f32 v84, v88, v89
	v_sub_f32_e32 v90, v90, v149
	v_sub_f32_e32 v91, v91, v149
	v_exp_f32_e32 v90, v90
	v_exp_f32_e32 v91, v91
	v_add_f32_e32 v128, v128, v90
	v_add_f32_e32 v236, v236, v91
	v_cvt_pk_bf16_f32 v85, v90, v91
	v_mfma_f32_32x32x16_bf16 v[196:211], v[184:187], v[96:99], v[196:211]
	ds_read_b128 v[172:175], v159 offset:34816
	ds_read_b128 v[176:179], v159 offset:34848
	ds_read_b128 v[180:183], v159 offset:34880
	ds_read_b128 v[184:187], v159 offset:34912
	v_sub_f32_e32 v92, v92, v149
	v_sub_f32_e32 v93, v93, v149
	v_exp_f32_e32 v92, v92
	v_exp_f32_e32 v93, v93
	v_add_f32_e32 v128, v128, v92
	v_add_f32_e32 v236, v236, v93
	v_cvt_pk_bf16_f32 v86, v92, v93
	v_sub_f32_e32 v94, v94, v149
	v_sub_f32_e32 v95, v95, v149
	v_exp_f32_e32 v94, v94
	v_exp_f32_e32 v95, v95
	v_add_f32_e32 v128, v128, v94
	v_add_f32_e32 v236, v236, v95
	v_cvt_pk_bf16_f32 v87, v94, v95
	s_waitcnt lgkmcnt(4)
	v_mfma_f32_32x32x16_bf16 v[212:227], v[188:191], v[108:111], 0
	v_sub_f32_e32 v64, v64, v149
	v_sub_f32_e32 v65, v65, v149
	v_exp_f32_e32 v64, v64
	v_exp_f32_e32 v65, v65
	v_add_f32_e32 v128, v128, v64
	v_add_f32_e32 v236, v236, v65
	v_cvt_pk_bf16_f32 v64, v64, v65
	v_sub_f32_e32 v66, v66, v149
	v_sub_f32_e32 v67, v67, v149
	v_exp_f32_e32 v66, v66
	v_exp_f32_e32 v67, v67
	v_add_f32_e32 v128, v128, v66
	v_add_f32_e32 v236, v236, v67
	v_cvt_pk_bf16_f32 v65, v66, v67
	v_mfma_f32_32x32x16_bf16 v[212:227], v[192:195], v[104:107], v[212:227]
	v_sub_f32_e32 v68, v68, v149
	v_sub_f32_e32 v69, v69, v149
	v_exp_f32_e32 v68, v68
	v_exp_f32_e32 v69, v69
	v_add_f32_e32 v128, v128, v68
	v_add_f32_e32 v236, v236, v69
	v_cvt_pk_bf16_f32 v66, v68, v69
	v_sub_f32_e32 v70, v70, v149
	v_sub_f32_e32 v71, v71, v149
	v_exp_f32_e32 v70, v70
	v_exp_f32_e32 v71, v71
	v_add_f32_e32 v128, v128, v70
	v_add_f32_e32 v236, v236, v71
	v_cvt_pk_bf16_f32 v67, v70, v71
	v_mfma_f32_32x32x16_bf16 v[212:227], v[228:231], v[100:103], v[212:227]
	v_sub_f32_e32 v72, v72, v149
	v_sub_f32_e32 v73, v73, v149
	v_exp_f32_e32 v72, v72
	v_exp_f32_e32 v73, v73
	v_add_f32_e32 v128, v128, v72
	v_add_f32_e32 v236, v236, v73
	v_cvt_pk_bf16_f32 v68, v72, v73
	v_sub_f32_e32 v74, v74, v149
	v_sub_f32_e32 v75, v75, v149
	v_exp_f32_e32 v74, v74
	v_exp_f32_e32 v75, v75
	v_add_f32_e32 v128, v128, v74
	v_add_f32_e32 v236, v236, v75
	v_cvt_pk_bf16_f32 v69, v74, v75
	v_mfma_f32_32x32x16_bf16 v[212:227], v[232:235], v[96:99], v[212:227]
	ds_read_b128 v[188:191], v159 offset:39424
	ds_read_b128 v[192:195], v159 offset:39456
	ds_read_b128 v[228:231], v159 offset:39488
	ds_read_b128 v[232:235], v159 offset:39520
	v_sub_f32_e32 v76, v76, v149
	v_sub_f32_e32 v77, v77, v149
	v_exp_f32_e32 v76, v76
	v_exp_f32_e32 v77, v77
	v_add_f32_e32 v128, v128, v76
	v_add_f32_e32 v236, v236, v77
	v_cvt_pk_bf16_f32 v70, v76, v77
	v_sub_f32_e32 v78, v78, v149
	v_sub_f32_e32 v79, v79, v149
	v_exp_f32_e32 v78, v78
	v_exp_f32_e32 v79, v79
	v_add_f32_e32 v128, v128, v78
	v_add_f32_e32 v236, v236, v79
	v_cvt_pk_bf16_f32 v71, v78, v79
	v_add_f32_e32 v128, v128, v236
	s_waitcnt lgkmcnt(4)
	v_mfma_f32_32x32x16_bf16 v[48:63], v[172:175], v[80:83], v[48:63]
	v_mfma_f32_32x32x16_bf16 v[48:63], v[176:179], v[84:87], v[48:63]
	v_max3_f32 v145, v196, v197, v198
	v_max3_f32 v237, v212, v213, v214
	v_max3_f32 v145, v145, v199, v200
	v_mfma_f32_32x32x16_bf16 v[48:63], v[180:183], v[64:67], v[48:63]
	v_max3_f32 v237, v237, v215, v216
	v_max3_f32 v145, v145, v201, v202
	v_max3_f32 v237, v237, v217, v218
	v_mfma_f32_32x32x16_bf16 v[48:63], v[184:187], v[68:71], v[48:63]
	v_max3_f32 v145, v145, v203, v204
	v_max3_f32 v237, v237, v219, v220
	v_max3_f32 v145, v145, v205, v206
	ds_read_b128 v[172:175], v159 offset:44032
	ds_read_b128 v[176:179], v159 offset:44064
	ds_read_b128 v[180:183], v159 offset:44096
	ds_read_b128 v[184:187], v159 offset:44128
	s_waitcnt lgkmcnt(4)
	v_mfma_f32_32x32x16_bf16 v[32:47], v[188:191], v[80:83], v[32:47]
	v_max3_f32 v237, v237, v221, v222
	v_max3_f32 v145, v145, v207, v208
	v_max3_f32 v237, v237, v223, v224
	v_mfma_f32_32x32x16_bf16 v[32:47], v[192:195], v[84:87], v[32:47]
	v_max3_f32 v145, v145, v209, v210
	v_max3_f32 v237, v237, v225, v226
	v_max_f32_e32 v145, v145, v211
	v_mfma_f32_32x32x16_bf16 v[32:47], v[228:231], v[64:67], v[32:47]
	v_max_f32_e32 v237, v237, v227
	v_max_f32_e32 v145, v145, v237
	ds_bpermute_b32 v237, v158, v145
	v_mfma_f32_32x32x16_bf16 v[32:47], v[232:235], v[68:71], v[32:47]
	v_add_u32_e32 v239, v131, v164
	s_waitcnt vmcnt(3)
	ds_write_b128 v239, v[116:119] offset:0
	ds_read_b128 v[188:191], v159 offset:48640
	ds_read_b128 v[192:195], v159 offset:48672
	ds_read_b128 v[228:231], v159 offset:48704
	ds_read_b128 v[232:235], v159 offset:48736
	s_waitcnt lgkmcnt(6)
	v_mfma_f32_32x32x16_bf16 v[16:31], v[172:175], v[80:83], v[16:31]
	v_add_u32_e32 v239, v131, v165
	s_waitcnt vmcnt(2)
	ds_write_b128 v239, v[112:115] offset:0
	v_mfma_f32_32x32x16_bf16 v[16:31], v[176:179], v[84:87], v[16:31]
	v_add_u32_e32 v239, v156, v166
	s_waitcnt vmcnt(1)
	ds_write_b128 v239, v[124:127] offset:53248
	v_mfma_f32_32x32x16_bf16 v[16:31], v[180:183], v[64:67], v[16:31]
	v_add_u32_e32 v239, v156, v167
	s_waitcnt vmcnt(0)
	ds_write_b128 v239, v[120:123] offset:53248
	v_mfma_f32_32x32x16_bf16 v[16:31], v[184:187], v[68:71], v[16:31]
	s_waitcnt lgkmcnt(8)
	v_max_f32_e32 v237, v145, v237
	v_add_f32_e32 v239, 0x41000000, v149
	v_max_f32_e32 v145, v149, v237
	v_sub_f32_e32 v238, v149, v145
	v_cmp_gt_f32_e32 vcc, v237, v239
	v_exp_f32_e32 v238, v238
	s_cbranch_vccz .Lat_keepm_2
	v_mov_b32_e32 v149, v145

; __device__ __forceinline__ unsigned cvt_pk_bf16(float lo, float hi) { unsigned r; asm volatile("v_cvt_pk_bf16_f32 %0, %1, %2" : "=v"(r) : "v"(lo), "v"(hi)); return r; }
; __device__ __forceinline__ void phase_attn(const Params& p, unsigned char* lds) {
;     ...
;             AT_QK(st, buf);
;             float mloc = st[0][0];
; #pragma unroll
;             for (int i = 0; i < 16; ++i) { mloc = fmaxf(mloc, st[0][i]); mloc = fmaxf(mloc, st[1][i]); }
;             mloc = fmaxf(mloc, __shfl_xor(mloc, 32));
;             const float mnew = fmaxf(mrun, mloc);
;             if (__builtin_amdgcn_ballot_w64(mnew > mrun) != 0ull) {
;                 const float alpha = __builtin_amdgcn_exp2f(mrun - mnew);
;                 lsum *= alpha;
; #pragma unroll
;                 for (int vb = 0; vb < 4; ++vb)
; #pragma unroll
;                     for (int i = 0; i < 16; ++i) ot[vb][i] *= alpha;
;             }
;             mrun = mnew;
;             bf16x8 P[2][2];
; #pragma unroll
;             for (int kb = 0; kb < 2; ++kb)
; #pragma unroll
;                 for (int s2 = 0; s2 < 2; ++s2) { u32x4 pk;
; #pragma unroll
;                     for (int jj = 0; jj < 4; ++jj) { const float p0 = __builtin_amdgcn_exp2f(st[kb][8 * s2 + 2 * jj] - mnew), p1 = __builtin_amdgcn_exp2f(st[kb][8 * s2 + 2 * jj + 1] - mnew); lsum += p0 + p1; pk[jj] = cvt_pk_bf16(p0, p1); }
;                     P[kb][s2] = __builtin_bit_cast(bf16x8, pk); }
;             {
;                 bf16x8 vf[2][4];
;     ...
;                 AT_LDV(0, 0);
; #pragma unroll
;                 for (int vb = 0; vb < 4; ++vb) {
;                     if (vb < 3) AT_LDV((vb + 1) & 1, vb + 1);
;                     __builtin_amdgcn_sched_barrier(0);
;                     __builtin_amdgcn_s_setprio(2);
; #pragma unroll
;                     for (int kb = 0; kb < 2; ++kb)
; #pragma unroll
;                         for (int s2 = 0; s2 < 2; ++s2) ot[vb] = __builtin_amdgcn_mfma_f32_32x32x16_bf16(vf[vb & 1][kb * 2 + s2], P[kb][s2], ot[vb], 0, 0, 0);
;                     __builtin_amdgcn_s_setprio(0);
;                     __builtin_amdgcn_sched_barrier(0);
;                 }
.Lat_norescale_3:
	v_mov_b32_e32 v236, 0
	v_mfma_f32_32x32x16_bf16 v[0:15], v[188:191], v[80:83], v[0:15]
	v_sub_f32_e32 v196, v196, v149
	v_sub_f32_e32 v197, v197, v149
	v_exp_f32_e32 v196, v196
	v_exp_f32_e32 v197, v197
	v_add_f32_e32 v128, v128, v196
	v_add_f32_e32 v236, v236, v197
	v_cvt_pk_bf16_f32 v196, v196, v197
	v_sub_f32_e32 v198, v198, v149
	v_sub_f32_e32 v199, v199, v149
	v_exp_f32_e32 v198, v198
	v_exp_f32_e32 v199, v199
	v_add_f32_e32 v128, v128, v198
	v_add_f32_e32 v236, v236, v199
	v_cvt_pk_bf16_f32 v197, v198, v199
	v_mfma_f32_32x32x16_bf16 v[0:15], v[192:195], v[84:87], v[0:15]
	v_sub_f32_e32 v200, v200, v149
	v_sub_f32_e32 v201, v201, v149
	v_exp_f32_e32 v200, v200
	v_exp_f32_e32 v201, v201
	v_add_f32_e32 v128, v128, v200
	v_add_f32_e32 v236, v236, v201
	v_cvt_pk_bf16_f32 v198, v200, v201
	v_sub_f32_e32 v202, v202, v149
	v_sub_f32_e32 v203, v203, v149
	v_exp_f32_e32 v202, v202
	v_exp_f32_e32 v203, v203
	v_add_f32_e32 v128, v128, v202
	v_add_f32_e32 v236, v236, v203
	v_cvt_pk_bf16_f32 v199, v202, v203
	v_mfma_f32_32x32x16_bf16 v[0:15], v[228:231], v[64:67], v[0:15]
	v_sub_f32_e32 v204, v204, v149
	v_sub_f32_e32 v205, v205, v149
	v_exp_f32_e32 v204, v204
	v_exp_f32_e32 v205, v205
	v_add_f32_e32 v128, v128, v204
	v_add_f32_e32 v236, v236, v205
	v_cvt_pk_bf16_f32 v200, v204, v205
	v_sub_f32_e32 v206, v206, v149
	v_sub_f32_e32 v207, v207, v149
	v_exp_f32_e32 v206, v206
	v_exp_f32_e32 v207, v207
	v_add_f32_e32 v128, v128, v206
	v_add_f32_e32 v236, v236, v207
	v_cvt_pk_bf16_f32 v201, v206, v207
	v_mfma_f32_32x32x16_bf16 v[0:15], v[232:235], v[68:71], v[0:15]
	ds_read_b128 v[188:191], v157 offset:8704
	ds_read_b128 v[192:195], v157 offset:8736
	ds_read_b128 v[228:231], v157 offset:8768
	ds_read_b128 v[232:235], v157 offset:8800
	v_sub_f32_e32 v208, v208, v149
	v_sub_f32_e32 v209, v209, v149
	v_exp_f32_e32 v208, v208
	v_exp_f32_e32 v209, v209
	v_add_f32_e32 v128, v128, v208
	v_add_f32_e32 v236, v236, v209
	v_cvt_pk_bf16_f32 v202, v208, v209
	v_sub_f32_e32 v210, v210, v149
	v_sub_f32_e32 v211, v211, v149
	v_exp_f32_e32 v210, v210
	v_exp_f32_e32 v211, v211
	v_add_f32_e32 v128, v128, v210
	v_add_f32_e32 v236, v236, v211
	v_cvt_pk_bf16_f32 v203, v210, v211
	s_waitcnt lgkmcnt(4)
	v_mfma_f32_32x32x16_bf16 v[80:95], v[172:175], v[108:111], 0
	v_sub_f32_e32 v212, v212, v149
	v_sub_f32_e32 v213, v213, v149
	v_exp_f32_e32 v212, v212
	v_exp_f32_e32 v213, v213
	v_add_f32_e32 v128, v128, v212
	v_add_f32_e32 v236, v236, v213
	v_cvt_pk_bf16_f32 v212, v212, v213
	v_mfma_f32_32x32x16_bf16 v[80:95], v[176:179], v[104:107], v[80:95]
	v_sub_f32_e32 v214, v214, v149
	v_sub_f32_e32 v215, v215, v149
	v_exp_f32_e32 v214, v214
	v_exp_f32_e32 v215, v215
	v_add_f32_e32 v128, v128, v214
	v_add_f32_e32 v236, v236, v215
	v_cvt_pk_bf16_f32 v213, v214, v215
	s_cbranch_vccz .Lat_norescale_4
	v_pk_mul_f32 v[14:15], v[14:15], v[238:239] op_sel_hi:[1,0]
	v_pk_mul_f32 v[12:13], v[12:13], v[238:239] op_sel_hi:[1,0]
	v_pk_mul_f32 v[10:11], v[10:11], v[238:239] op_sel_hi:[1,0]
	v_pk_mul_f32 v[8:9], v[8:9], v[238:239] op_sel_hi:[1,0]
	v_pk_mul_f32 v[6:7], v[6:7], v[238:239] op_sel_hi:[1,0]
	v_pk_mul_f32 v[4:5], v[4:5], v[238:239] op_sel_hi:[1,0]
	v_pk_mul_f32 v[2:3], v[2:3], v[238:239] op_sel_hi:[1,0]
	v_pk_mul_f32 v[0:1], v[0:1], v[238:239] op_sel_hi:[1,0]
; __device__ __forceinline__ unsigned cvt_pk_bf16(float lo, float hi) { unsigned r; asm volatile("v_cvt_pk_bf16_f32 %0, %1, %2" : "=v"(r) : "v"(lo), "v"(hi)); return r; }
; __device__ __forceinline__ void phase_attn(const Params& p, unsigned char* lds) {
;     ...
;             AT_QK(st, buf);
;             float mloc = st[0][0];
; #pragma unroll
;             for (int i = 0; i < 16; ++i) { mloc = fmaxf(mloc, st[0][i]); mloc = fmaxf(mloc, st[1][i]); }
;             mloc = fmaxf(mloc, __shfl_xor(mloc, 32));
;             const float mnew = fmaxf(mrun, mloc);
;             if (__builtin_amdgcn_ballot_w64(mnew > mrun) != 0ull) {
;                 const float alpha = __builtin_amdgcn_exp2f(mrun - mnew);
;                 lsum *= alpha;
; #pragma unroll
;                 for (int vb = 0; vb < 4; ++vb)
; #pragma unroll
;                     for (int i = 0; i < 16; ++i) ot[vb][i] *= alpha;
;             }
;             mrun = mnew;
;             bf16x8 P[2][2];
; #pragma unroll
;             for (int kb = 0; kb < 2; ++kb)
; #pragma unroll
;                 for (int s2 = 0; s2 < 2; ++s2) { u32x4 pk;
; #pragma unroll
;                     for (int jj = 0; jj < 4; ++jj) { const float p0 = __builtin_amdgcn_exp2f(st[kb][8 * s2 + 2 * jj] - mnew), p1 = __builtin_amdgcn_exp2f(st[kb][8 * s2 + 2 * jj + 1] - mnew); lsum += p0 + p1; pk[jj] = cvt_pk_bf16(p0, p1); }
;                     P[kb][s2] = __builtin_bit_cast(bf16x8, pk); }
;             {
;                 bf16x8 vf[2][4];
;     ...
;                 AT_LDV(0, 0);
; #pragma unroll
;                 for (int vb = 0; vb < 4; ++vb) {
;                     if (vb < 3) AT_LDV((vb + 1) & 1, vb + 1);
;                     __builtin_amdgcn_sched_barrier(0);
;                     __builtin_amdgcn_s_setprio(2);
; #pragma unroll
;                     for (int kb = 0; kb < 2; ++kb)
; #pragma unroll
;                         for (int s2 = 0; s2 < 2; ++s2) ot[vb] = __builtin_amdgcn_mfma_f32_32x32x16_bf16(vf[vb & 1][kb * 2 + s2], P[kb][s2], ot[vb], 0, 0, 0);
;                     __builtin_amdgcn_s_setprio(0);
;                     __builtin_amdgcn_sched_barrier(0);
;                 }
;     ...
;             }
;             if (kt + 1 < 64) { AT_STOREK(buf ^ 1); AT_STOREV(buf ^ 1); }
.Lat_norescale_4:
	v_mfma_f32_32x32x16_bf16 v[80:95], v[180:183], v[100:103], v[80:95]
	v_sub_f32_e32 v216, v216, v149
	v_sub_f32_e32 v217, v217, v149
	v_exp_f32_e32 v216, v216
	v_exp_f32_e32 v217, v217
	v_add_f32_e32 v128, v128, v216
	v_add_f32_e32 v236, v236, v217
	v_cvt_pk_bf16_f32 v214, v216, v217
	v_mfma_f32_32x32x16_bf16 v[80:95], v[184:187], v[96:99], v[80:95]
	ds_read_b128 v[172:175], v147 offset:34816
	ds_read_b128 v[176:179], v147 offset:34848
	ds_read_b128 v[180:183], v147 offset:34880
	ds_read_b128 v[184:187], v147 offset:34912
	v_sub_f32_e32 v218, v218, v149
	v_sub_f32_e32 v219, v219, v149
	v_exp_f32_e32 v218, v218
	v_exp_f32_e32 v219, v219
	v_add_f32_e32 v128, v128, v218
	v_add_f32_e32 v236, v236, v219
	v_cvt_pk_bf16_f32 v215, v218, v219
	s_waitcnt lgkmcnt(4)
	v_mfma_f32_32x32x16_bf16 v[64:79], v[188:191], v[108:111], 0
	v_sub_f32_e32 v220, v220, v149
	v_sub_f32_e32 v221, v221, v149
	v_exp_f32_e32 v220, v220
	v_exp_f32_e32 v221, v221
	v_add_f32_e32 v128, v128, v220
	v_add_f32_e32 v236, v236, v221
	v_cvt_pk_bf16_f32 v216, v220, v221
	v_mfma_f32_32x32x16_bf16 v[64:79], v[192:195], v[104:107], v[64:79]
	v_sub_f32_e32 v222, v222, v149
	v_sub_f32_e32 v223, v223, v149
	v_exp_f32_e32 v222, v222
	v_exp_f32_e32 v223, v223
	v_add_f32_e32 v128, v128, v222
	v_add_f32_e32 v236, v236, v223
	v_cvt_pk_bf16_f32 v217, v222, v223
	v_mfma_f32_32x32x16_bf16 v[64:79], v[228:231], v[100:103], v[64:79]
	v_sub_f32_e32 v224, v224, v149
	v_sub_f32_e32 v225, v225, v149
	v_exp_f32_e32 v224, v224
	v_exp_f32_e32 v225, v225
	v_add_f32_e32 v128, v128, v224
	v_add_f32_e32 v236, v236, v225
	v_cvt_pk_bf16_f32 v218, v224, v225
	v_mfma_f32_32x32x16_bf16 v[64:79], v[232:235], v[96:99], v[64:79]
	ds_read_b128 v[188:191], v147 offset:39424
	ds_read_b128 v[192:195], v147 offset:39456
	ds_read_b128 v[228:231], v147 offset:39488
	ds_read_b128 v[232:235], v147 offset:39520
	v_sub_f32_e32 v226, v226, v149
	v_sub_f32_e32 v227, v227, v149
	v_exp_f32_e32 v226, v226
	v_exp_f32_e32 v227, v227
	v_add_f32_e32 v128, v128, v226
	v_add_f32_e32 v236, v236, v227
	v_cvt_pk_bf16_f32 v219, v226, v227
	v_add_f32_e32 v128, v128, v236
	s_waitcnt lgkmcnt(4)
	v_mfma_f32_32x32x16_bf16 v[48:63], v[172:175], v[196:199], v[48:63]
	v_mfma_f32_32x32x16_bf16 v[48:63], v[176:179], v[200:203], v[48:63]
	v_max3_f32 v145, v80, v81, v82
	v_max3_f32 v237, v64, v65, v66
	v_max3_f32 v145, v145, v83, v84
	v_mfma_f32_32x32x16_bf16 v[48:63], v[180:183], v[212:215], v[48:63]
	v_max3_f32 v237, v237, v67, v68
	v_max3_f32 v145, v145, v85, v86
	v_max3_f32 v237, v237, v69, v70
	v_mfma_f32_32x32x16_bf16 v[48:63], v[184:187], v[216:219], v[48:63]
	v_max3_f32 v145, v145, v87, v88
	v_max3_f32 v237, v237, v71, v72
	v_max3_f32 v145, v145, v89, v90
	ds_read_b128 v[172:175], v147 offset:44032
	ds_read_b128 v[176:179], v147 offset:44064
	ds_read_b128 v[180:183], v147 offset:44096
	ds_read_b128 v[184:187], v147 offset:44128
	s_waitcnt lgkmcnt(4)
	v_mfma_f32_32x32x16_bf16 v[32:47], v[188:191], v[196:199], v[32:47]
	v_max3_f32 v237, v237, v73, v74
	v_max3_f32 v145, v145, v91, v92
	v_max3_f32 v237, v237, v75, v76
	v_mfma_f32_32x32x16_bf16 v[32:47], v[192:195], v[200:203], v[32:47]
	v_max3_f32 v145, v145, v93, v94
	v_max3_f32 v237, v237, v77, v78
	v_max_f32_e32 v145, v145, v95
	v_mfma_f32_32x32x16_bf16 v[32:47], v[228:231], v[212:215], v[32:47]
	v_max_f32_e32 v237, v237, v79
	v_max_f32_e32 v145, v145, v237
	ds_bpermute_b32 v237, v158, v145
	v_mfma_f32_32x32x16_bf16 v[32:47], v[232:235], v[216:219], v[32:47]
	v_add_u32_e32 v239, v131, v164
	s_waitcnt vmcnt(3)
	ds_write_b128 v239, v[116:119] offset:17408
	ds_read_b128 v[188:191], v147 offset:48640
	ds_read_b128 v[192:195], v147 offset:48672
	ds_read_b128 v[228:231], v147 offset:48704
	ds_read_b128 v[232:235], v147 offset:48736
	s_waitcnt lgkmcnt(6)
	v_mfma_f32_32x32x16_bf16 v[16:31], v[172:175], v[196:199], v[16:31]
	v_add_u32_e32 v239, v131, v165
	s_waitcnt vmcnt(2)
	ds_write_b128 v239, v[112:115] offset:17408
	v_mfma_f32_32x32x16_bf16 v[16:31], v[176:179], v[200:203], v[16:31]
	v_add_u32_e32 v239, v156, v166
	s_waitcnt vmcnt(1)
	ds_write_b128 v239, v[124:127] offset:34816
	v_mfma_f32_32x32x16_bf16 v[16:31], v[180:183], v[212:215], v[16:31]
	v_add_u32_e32 v239, v156, v167
	s_waitcnt vmcnt(0)
	ds_write_b128 v239, v[120:123] offset:34816
	v_mfma_f32_32x32x16_bf16 v[16:31], v[184:187], v[216:219], v[16:31]
	s_waitcnt lgkmcnt(8)
	v_max_f32_e32 v237, v145, v237
	v_add_f32_e32 v239, 0x41000000, v149
	v_max_f32_e32 v145, v149, v237
	v_sub_f32_e32 v238, v149, v145
	v_cmp_gt_f32_e32 vcc, v237, v239
	v_exp_f32_e32 v238, v238
	s_cbranch_vccz .Lat_keepm_5
	v_mov_b32_e32 v149, v145

; __device__ __forceinline__ unsigned cvt_pk_bf16(float lo, float hi) { unsigned r; asm volatile("v_cvt_pk_bf16_f32 %0, %1, %2" : "=v"(r) : "v"(lo), "v"(hi)); return r; }
; __device__ __forceinline__ void phase_attn(const Params& p, unsigned char* lds) {
;     ...
;             AT_QK(st, buf);
;             float mloc = st[0][0];
; #pragma unroll
;             for (int i = 0; i < 16; ++i) { mloc = fmaxf(mloc, st[0][i]); mloc = fmaxf(mloc, st[1][i]); }
;             mloc = fmaxf(mloc, __shfl_xor(mloc, 32));
;             const float mnew = fmaxf(mrun, mloc);
;             if (__builtin_amdgcn_ballot_w64(mnew > mrun) != 0ull) {
;                 const float alpha = __builtin_amdgcn_exp2f(mrun - mnew);
;                 lsum *= alpha;
; #pragma unroll
;                 for (int vb = 0; vb < 4; ++vb)
; #pragma unroll
;                     for (int i = 0; i < 16; ++i) ot[vb][i] *= alpha;
;             }
;             mrun = mnew;
;             bf16x8 P[2][2];
; #pragma unroll
;             for (int kb = 0; kb < 2; ++kb)
; #pragma unroll
;                 for (int s2 = 0; s2 < 2; ++s2) { u32x4 pk;
; #pragma unroll
;                     for (int jj = 0; jj < 4; ++jj) { const float p0 = __builtin_amdgcn_exp2f(st[kb][8 * s2 + 2 * jj] - mnew), p1 = __builtin_amdgcn_exp2f(st[kb][8 * s2 + 2 * jj + 1] - mnew); lsum += p0 + p1; pk[jj] = cvt_pk_bf16(p0, p1); }
;                     P[kb][s2] = __builtin_bit_cast(bf16x8, pk); }
;             {
;                 bf16x8 vf[2][4];
;     ...
;                 AT_LDV(0, 0);
; #pragma unroll
;                 for (int vb = 0; vb < 4; ++vb) {
;                     if (vb < 3) AT_LDV((vb + 1) & 1, vb + 1);
;                     __builtin_amdgcn_sched_barrier(0);
;                     __builtin_amdgcn_s_setprio(2);
; #pragma unroll
;                     for (int kb = 0; kb < 2; ++kb)
; #pragma unroll
;                         for (int s2 = 0; s2 < 2; ++s2) ot[vb] = __builtin_amdgcn_mfma_f32_32x32x16_bf16(vf[vb & 1][kb * 2 + s2], P[kb][s2], ot[vb], 0, 0, 0);
;                     __builtin_amdgcn_s_setprio(0);
;                     __builtin_amdgcn_sched_barrier(0);
;                 }
.Lat_norescale_6:
	v_mov_b32_e32 v236, 0
	v_mfma_f32_32x32x16_bf16 v[0:15], v[188:191], v[196:199], v[0:15]
	v_sub_f32_e32 v80, v80, v149
	v_sub_f32_e32 v81, v81, v149
	v_exp_f32_e32 v80, v80
	v_exp_f32_e32 v81, v81
	v_add_f32_e32 v128, v128, v80
	v_add_f32_e32 v236, v236, v81
	v_cvt_pk_bf16_f32 v80, v80, v81
	v_sub_f32_e32 v82, v82, v149
	v_sub_f32_e32 v83, v83, v149
	v_exp_f32_e32 v82, v82
	v_exp_f32_e32 v83, v83
	v_add_f32_e32 v128, v128, v82
	v_add_f32_e32 v236, v236, v83
	v_cvt_pk_bf16_f32 v81, v82, v83
	v_mfma_f32_32x32x16_bf16 v[0:15], v[192:195], v[200:203], v[0:15]
	v_sub_f32_e32 v84, v84, v149
	v_sub_f32_e32 v85, v85, v149
	v_exp_f32_e32 v84, v84
	v_exp_f32_e32 v85, v85
	v_add_f32_e32 v128, v128, v84
	v_add_f32_e32 v236, v236, v85
	v_cvt_pk_bf16_f32 v82, v84, v85
	v_sub_f32_e32 v86, v86, v149
	v_sub_f32_e32 v87, v87, v149
	v_exp_f32_e32 v86, v86
	v_exp_f32_e32 v87, v87
	v_add_f32_e32 v128, v128, v86
	v_add_f32_e32 v236, v236, v87
	v_cvt_pk_bf16_f32 v83, v86, v87
	v_mfma_f32_32x32x16_bf16 v[0:15], v[228:231], v[212:215], v[0:15]
	v_sub_f32_e32 v88, v88, v149
	v_sub_f32_e32 v89, v89, v149
	v_exp_f32_e32 v88, v88
	v_exp_f32_e32 v89, v89
	v_add_f32_e32 v128, v128, v88
	v_add_f32_e32 v236, v236, v89
	v_cvt_pk_bf16_f32 v84, v88, v89
	v_sub_f32_e32 v90, v90, v149
	v_sub_f32_e32 v91, v91, v149
	v_exp_f32_e32 v90, v90
	v_exp_f32_e32 v91, v91
	v_add_f32_e32 v128, v128, v90
	v_add_f32_e32 v236, v236, v91
	v_cvt_pk_bf16_f32 v85, v90, v91
	v_mfma_f32_32x32x16_bf16 v[0:15], v[232:235], v[216:219], v[0:15]
	ds_read_b128 v[188:191], v157 offset:26112
	ds_read_b128 v[192:195], v157 offset:26144
	ds_read_b128 v[228:231], v157 offset:26176
	ds_read_b128 v[232:235], v157 offset:26208
	v_sub_f32_e32 v92, v92, v149
	v_sub_f32_e32 v93, v93, v149
	v_exp_f32_e32 v92, v92
	v_exp_f32_e32 v93, v93
	v_add_f32_e32 v128, v128, v92
	v_add_f32_e32 v236, v236, v93
	v_cvt_pk_bf16_f32 v86, v92, v93
	v_sub_f32_e32 v94, v94, v149
	v_sub_f32_e32 v95, v95, v149
	v_exp_f32_e32 v94, v94
	v_exp_f32_e32 v95, v95
	v_add_f32_e32 v128, v128, v94
	v_add_f32_e32 v236, v236, v95
	v_cvt_pk_bf16_f32 v87, v94, v95
	s_waitcnt lgkmcnt(4)
	v_mfma_f32_32x32x16_bf16 v[196:211], v[172:175], v[108:111], 0
	v_sub_f32_e32 v64, v64, v149
	v_sub_f32_e32 v65, v65, v149
	v_exp_f32_e32 v64, v64
	v_exp_f32_e32 v65, v65
	v_add_f32_e32 v128, v128, v64
	v_add_f32_e32 v236, v236, v65
	v_cvt_pk_bf16_f32 v64, v64, v65
	v_mfma_f32_32x32x16_bf16 v[196:211], v[176:179], v[104:107], v[196:211]
	v_sub_f32_e32 v66, v66, v149
	v_sub_f32_e32 v67, v67, v149
	v_exp_f32_e32 v66, v66
	v_exp_f32_e32 v67, v67
	v_add_f32_e32 v128, v128, v66
	v_add_f32_e32 v236, v236, v67
	v_cvt_pk_bf16_f32 v65, v66, v67
	s_cbranch_vccz .Lat_norescale_7
	v_pk_mul_f32 v[14:15], v[14:15], v[238:239] op_sel_hi:[1,0]
	v_pk_mul_f32 v[12:13], v[12:13], v[238:239] op_sel_hi:[1,0]
	v_pk_mul_f32 v[10:11], v[10:11], v[238:239] op_sel_hi:[1,0]
	v_pk_mul_f32 v[8:9], v[8:9], v[238:239] op_sel_hi:[1,0]
	v_pk_mul_f32 v[6:7], v[6:7], v[238:239] op_sel_hi:[1,0]
	v_pk_mul_f32 v[4:5], v[4:5], v[238:239] op_sel_hi:[1,0]
	v_pk_mul_f32 v[2:3], v[2:3], v[238:239] op_sel_hi:[1,0]
	v_pk_mul_f32 v[0:1], v[0:1], v[238:239] op_sel_hi:[1,0]
; __device__ __forceinline__ unsigned cvt_pk_bf16(float lo, float hi) { unsigned r; asm volatile("v_cvt_pk_bf16_f32 %0, %1, %2" : "=v"(r) : "v"(lo), "v"(hi)); return r; }
; __device__ __forceinline__ void phase_attn(const Params& p, unsigned char* lds) {
;     ...
;             AT_QK(st, buf);
;             float mloc = st[0][0];
; #pragma unroll
;             for (int i = 0; i < 16; ++i) { mloc = fmaxf(mloc, st[0][i]); mloc = fmaxf(mloc, st[1][i]); }
;             mloc = fmaxf(mloc, __shfl_xor(mloc, 32));
;             const float mnew = fmaxf(mrun, mloc);
;             if (__builtin_amdgcn_ballot_w64(mnew > mrun) != 0ull) {
;                 const float alpha = __builtin_amdgcn_exp2f(mrun - mnew);
;                 lsum *= alpha;
; #pragma unroll
;                 for (int vb = 0; vb < 4; ++vb)
; #pragma unroll
;                     for (int i = 0; i < 16; ++i) ot[vb][i] *= alpha;
;             }
;             mrun = mnew;
;             bf16x8 P[2][2];
; #pragma unroll
;             for (int kb = 0; kb < 2; ++kb)
; #pragma unroll
;                 for (int s2 = 0; s2 < 2; ++s2) { u32x4 pk;
; #pragma unroll
;                     for (int jj = 0; jj < 4; ++jj) { const float p0 = __builtin_amdgcn_exp2f(st[kb][8 * s2 + 2 * jj] - mnew), p1 = __builtin_amdgcn_exp2f(st[kb][8 * s2 + 2 * jj + 1] - mnew); lsum += p0 + p1; pk[jj] = cvt_pk_bf16(p0, p1); }
;                     P[kb][s2] = __builtin_bit_cast(bf16x8, pk); }
;             {
;                 bf16x8 vf[2][4];
;     ...
;                 AT_LDV(0, 0);
; #pragma unroll
;                 for (int vb = 0; vb < 4; ++vb) {
;                     if (vb < 3) AT_LDV((vb + 1) & 1, vb + 1);
;                     __builtin_amdgcn_sched_barrier(0);
;                     __builtin_amdgcn_s_setprio(2);
; #pragma unroll
;                     for (int kb = 0; kb < 2; ++kb)
; #pragma unroll
;                         for (int s2 = 0; s2 < 2; ++s2) ot[vb] = __builtin_amdgcn_mfma_f32_32x32x16_bf16(vf[vb & 1][kb * 2 + s2], P[kb][s2], ot[vb], 0, 0, 0);
;                     __builtin_amdgcn_s_setprio(0);
;                     __builtin_amdgcn_sched_barrier(0);
;                 }
;     ...
;             }
;             if (kt + 1 < 64) { AT_STOREK(buf ^ 1); AT_STOREV(buf ^ 1); }
.Lat_norescale_7:
	v_mfma_f32_32x32x16_bf16 v[196:211], v[180:183], v[100:103], v[196:211]
	v_sub_f32_e32 v68, v68, v149
	v_sub_f32_e32 v69, v69, v149
	v_exp_f32_e32 v68, v68
	v_exp_f32_e32 v69, v69
	v_add_f32_e32 v128, v128, v68
	v_add_f32_e32 v236, v236, v69
	v_cvt_pk_bf16_f32 v66, v68, v69
	v_mfma_f32_32x32x16_bf16 v[196:211], v[184:187], v[96:99], v[196:211]
	ds_read_b128 v[172:175], v159 offset:34816
	ds_read_b128 v[176:179], v159 offset:34848
	ds_read_b128 v[180:183], v159 offset:34880
	ds_read_b128 v[184:187], v159 offset:34912
	v_sub_f32_e32 v70, v70, v149
	v_sub_f32_e32 v71, v71, v149
	v_exp_f32_e32 v70, v70
	v_exp_f32_e32 v71, v71
	v_add_f32_e32 v128, v128, v70
	v_add_f32_e32 v236, v236, v71
	v_cvt_pk_bf16_f32 v67, v70, v71
	s_waitcnt lgkmcnt(4)
	v_mfma_f32_32x32x16_bf16 v[212:227], v[188:191], v[108:111], 0
	v_sub_f32_e32 v72, v72, v149
	v_sub_f32_e32 v73, v73, v149
	v_exp_f32_e32 v72, v72
	v_exp_f32_e32 v73, v73
	v_add_f32_e32 v128, v128, v72
	v_add_f32_e32 v236, v236, v73
	v_cvt_pk_bf16_f32 v68, v72, v73
	v_mfma_f32_32x32x16_bf16 v[212:227], v[192:195], v[104:107], v[212:227]
	v_sub_f32_e32 v74, v74, v149
	v_sub_f32_e32 v75, v75, v149
	v_exp_f32_e32 v74, v74
	v_exp_f32_e32 v75, v75
	v_add_f32_e32 v128, v128, v74
	v_add_f32_e32 v236, v236, v75
	v_cvt_pk_bf16_f32 v69, v74, v75
	v_mfma_f32_32x32x16_bf16 v[212:227], v[228:231], v[100:103], v[212:227]
	v_sub_f32_e32 v76, v76, v149
	v_sub_f32_e32 v77, v77, v149
	v_exp_f32_e32 v76, v76
	v_exp_f32_e32 v77, v77
	v_add_f32_e32 v128, v128, v76
	v_add_f32_e32 v236, v236, v77
	v_cvt_pk_bf16_f32 v70, v76, v77
	v_mfma_f32_32x32x16_bf16 v[212:227], v[232:235], v[96:99], v[212:227]
	ds_read_b128 v[188:191], v159 offset:39424
	ds_read_b128 v[192:195], v159 offset:39456
	ds_read_b128 v[228:231], v159 offset:39488
	ds_read_b128 v[232:235], v159 offset:39520
	v_sub_f32_e32 v78, v78, v149
	v_sub_f32_e32 v79, v79, v149
	v_exp_f32_e32 v78, v78
	v_exp_f32_e32 v79, v79
	v_add_f32_e32 v128, v128, v78
	v_add_f32_e32 v236, v236, v79
	v_cvt_pk_bf16_f32 v71, v78, v79
	v_add_f32_e32 v128, v128, v236
	s_waitcnt lgkmcnt(4)
	v_mfma_f32_32x32x16_bf16 v[48:63], v[172:175], v[80:83], v[48:63]
	v_mfma_f32_32x32x16_bf16 v[48:63], v[176:179], v[84:87], v[48:63]
	v_max3_f32 v145, v196, v197, v198
	v_max3_f32 v237, v212, v213, v214
	v_max3_f32 v145, v145, v199, v200
	v_mfma_f32_32x32x16_bf16 v[48:63], v[180:183], v[64:67], v[48:63]
	v_max3_f32 v237, v237, v215, v216
	v_max3_f32 v145, v145, v201, v202
	v_max3_f32 v237, v237, v217, v218
	v_mfma_f32_32x32x16_bf16 v[48:63], v[184:187], v[68:71], v[48:63]
	v_max3_f32 v145, v145, v203, v204
	v_max3_f32 v237, v237, v219, v220
	v_max3_f32 v145, v145, v205, v206
	ds_read_b128 v[172:175], v159 offset:44032
	ds_read_b128 v[176:179], v159 offset:44064
	ds_read_b128 v[180:183], v159 offset:44096
	ds_read_b128 v[184:187], v159 offset:44128
	s_waitcnt lgkmcnt(4)
	v_mfma_f32_32x32x16_bf16 v[32:47], v[188:191], v[80:83], v[32:47]
	v_max3_f32 v237, v237, v221, v222
	v_max3_f32 v145, v145, v207, v208
	v_max3_f32 v237, v237, v223, v224
	v_mfma_f32_32x32x16_bf16 v[32:47], v[192:195], v[84:87], v[32:47]
	v_max3_f32 v145, v145, v209, v210
	v_max3_f32 v237, v237, v225, v226
	v_max_f32_e32 v145, v145, v211
	v_mfma_f32_32x32x16_bf16 v[32:47], v[228:231], v[64:67], v[32:47]
	v_max_f32_e32 v237, v237, v227
	v_max_f32_e32 v145, v145, v237
	ds_bpermute_b32 v237, v158, v145
	v_mfma_f32_32x32x16_bf16 v[32:47], v[232:235], v[68:71], v[32:47]
	v_add_u32_e32 v239, v131, v164
	s_waitcnt vmcnt(3)
	ds_write_b128 v239, v[116:119] offset:0
	ds_read_b128 v[188:191], v159 offset:48640
	ds_read_b128 v[192:195], v159 offset:48672
	ds_read_b128 v[228:231], v159 offset:48704
	ds_read_b128 v[232:235], v159 offset:48736
	s_waitcnt lgkmcnt(6)
	v_mfma_f32_32x32x16_bf16 v[16:31], v[172:175], v[80:83], v[16:31]
	v_add_u32_e32 v239, v131, v165
	s_waitcnt vmcnt(2)
	ds_write_b128 v239, v[112:115] offset:0
	v_mfma_f32_32x32x16_bf16 v[16:31], v[176:179], v[84:87], v[16:31]
	v_add_u32_e32 v239, v156, v166
	s_waitcnt vmcnt(1)
	ds_write_b128 v239, v[124:127] offset:53248
	v_mfma_f32_32x32x16_bf16 v[16:31], v[180:183], v[64:67], v[16:31]
	v_add_u32_e32 v239, v156, v167
	s_waitcnt vmcnt(0)
	ds_write_b128 v239, v[120:123] offset:53248
	v_mfma_f32_32x32x16_bf16 v[16:31], v[184:187], v[68:71], v[16:31]
	s_waitcnt lgkmcnt(8)
	v_max_f32_e32 v237, v145, v237
	v_add_f32_e32 v239, 0x41000000, v149
	v_max_f32_e32 v145, v149, v237
	v_sub_f32_e32 v238, v149, v145
	v_cmp_gt_f32_e32 vcc, v237, v239
	v_exp_f32_e32 v238, v238
	s_cbranch_vccz .Lat_keepm_8
	v_mov_b32_e32 v149, v145

; #define AT_STOREK(buf) do { _Pragma("unroll") for (int i_ = 0; i_ < 2; ++i_) { const int id_ = tid + 512 * i_; \
;             *(u32x4*)(sKt + (buf) * 8704 + (id_ >> 4) * 136 + (id_ & 15) * 8) = kr[i_]; } } while (0)
; #define AT_STOREV(buf) do { _Pragma("unroll") for (int i_ = 0; i_ < 2; ++i_) { const int id_ = tid + 512 * i_; \
;             *(u32x4*)(sVt + (buf) * 9216 + (id_ >> 3) * 72 + (id_ & 7) * 8) = vr[i_]; } } while (0)
; #define AT_LDV(set, vb) do { _Pragma("unroll") for (int kb = 0; kb < 2; ++kb) _Pragma("unroll") for (int s2 = 0; s2 < 2; ++s2) \
;                     vf[set][kb * 2 + s2] = *(const bf16x8*)(sVt + buf * 9216 + (32 * (vb) + ql) * 72 + 32 * kb + 16 * s2 + 8 * g); } while (0)
; __device__ __forceinline__ void phase_attn(const Params& p, unsigned char* lds) {
;     ...
;                 AT_LDV(0, 0);
; #pragma unroll
;                 for (int vb = 0; vb < 4; ++vb) {
;                     if (vb < 3) AT_LDV((vb + 1) & 1, vb + 1);
;                     __builtin_amdgcn_sched_barrier(0);
;                     __builtin_amdgcn_s_setprio(2);
; #pragma unroll
;                     for (int kb = 0; kb < 2; ++kb)
; #pragma unroll
;                         for (int s2 = 0; s2 < 2; ++s2) ot[vb] = __builtin_amdgcn_mfma_f32_32x32x16_bf16(vf[vb & 1][kb * 2 + s2], P[kb][s2], ot[vb], 0, 0, 0);
;                     __builtin_amdgcn_s_setprio(0);
;                     __builtin_amdgcn_sched_barrier(0);
;                 }
;     ...
;             }
;             if (kt + 1 < 64) { AT_STOREK(buf ^ 1); AT_STOREV(buf ^ 1); }
;             __syncthreads();
;         }
;     ...
;         lsum += __shfl_xor(lsum, 32);
;         const float inv = 1.0f / lsum;
;         if (cmap == 1) {
; #pragma unroll
;             for (int vb = 0; vb < 4; ++vb)
; #pragma unroll
;                 for (int i = 0; i < 16; ++i) ex[(vb * 16 + i) * 256 + qsub * 64 + lane] = ot[vb][i] * inv;
.Lat_norescale_10:
	ds_read_b128 v[172:175], v147 offset:34816
	ds_read_b128 v[176:179], v147 offset:34848
	ds_read_b128 v[180:183], v147 offset:34880
	ds_read_b128 v[184:187], v147 offset:34912
	ds_read_b128 v[188:191], v147 offset:39424
	ds_read_b128 v[192:195], v147 offset:39456
	ds_read_b128 v[228:231], v147 offset:39488
	ds_read_b128 v[232:235], v147 offset:39520
	v_add_f32_e32 v128, v128, v236
	s_waitcnt lgkmcnt(4)
	v_mfma_f32_32x32x16_bf16 v[48:63], v[172:175], v[196:199], v[48:63]
	v_mfma_f32_32x32x16_bf16 v[48:63], v[176:179], v[200:203], v[48:63]
	v_mfma_f32_32x32x16_bf16 v[48:63], v[180:183], v[212:215], v[48:63]
	v_mfma_f32_32x32x16_bf16 v[48:63], v[184:187], v[216:219], v[48:63]
	ds_read_b128 v[172:175], v147 offset:44032
	ds_read_b128 v[176:179], v147 offset:44064
	ds_read_b128 v[180:183], v147 offset:44096
	ds_read_b128 v[184:187], v147 offset:44128
	s_waitcnt lgkmcnt(4)
	v_mfma_f32_32x32x16_bf16 v[32:47], v[188:191], v[196:199], v[32:47]
	v_mfma_f32_32x32x16_bf16 v[32:47], v[192:195], v[200:203], v[32:47]
	v_mfma_f32_32x32x16_bf16 v[32:47], v[228:231], v[212:215], v[32:47]
	v_mfma_f32_32x32x16_bf16 v[32:47], v[232:235], v[216:219], v[32:47]
	ds_read_b128 v[188:191], v147 offset:48640
	ds_read_b128 v[192:195], v147 offset:48672
	ds_read_b128 v[228:231], v147 offset:48704
	ds_read_b128 v[232:235], v147 offset:48736
	s_waitcnt lgkmcnt(4)
	v_mfma_f32_32x32x16_bf16 v[16:31], v[172:175], v[196:199], v[16:31]
	v_mfma_f32_32x32x16_bf16 v[16:31], v[176:179], v[200:203], v[16:31]
	v_mfma_f32_32x32x16_bf16 v[16:31], v[180:183], v[212:215], v[16:31]
	v_mfma_f32_32x32x16_bf16 v[16:31], v[184:187], v[216:219], v[16:31]
	s_waitcnt lgkmcnt(0)
	v_mfma_f32_32x32x16_bf16 v[0:15], v[188:191], v[196:199], v[0:15]
	v_mfma_f32_32x32x16_bf16 v[0:15], v[192:195], v[200:203], v[0:15]
	v_mfma_f32_32x32x16_bf16 v[0:15], v[228:231], v[212:215], v[0:15]
	v_mfma_f32_32x32x16_bf16 v[0:15], v[232:235], v[216:219], v[0:15]
	v_mov_b32_e32 v64, v128
	ds_bpermute_b32 v65, v158, v64
	s_waitcnt lgkmcnt(0)
	s_barrier
	v_add_f32_e32 v64, v64, v65
	v_rcp_f32_e32 v66, v64
	s_nop 0
	v_fma_f32 v68, -v64, v66, 1.0
	v_fma_f32 v65, v68, v66, v66
	v_div_fixup_f32 v64, v65, v64, 1.0
	s_and_saveexec_b64 s[20:21], s[4:5]
	s_cbranch_execz .LBB0_2029
	v_mul_f32_e32 v65, v48, v64
	v_mul_f32_e32 v66, v49, v64
	ds_write2st64_b32 v160, v65, v66 offset1:4
	v_mul_f32_e32 v65, v50, v64
	v_mul_f32_e32 v66, v51, v64
	ds_write2st64_b32 v160, v65, v66 offset0:8 offset1:12
	v_mul_f32_e32 v65, v52, v64
	v_mul_f32_e32 v66, v53, v64
	ds_write2st64_b32 v160, v65, v66 offset0:16 offset1:20
	v_mul_f32_e32 v65, v54, v64
	v_mul_f32_e32 v66, v55, v64
	ds_write2st64_b32 v160, v65, v66 offset0:24 offset1:28
	v_mul_f32_e32 v65, v56, v64
	v_mul_f32_e32 v66, v57, v64
	ds_write2st64_b32 v160, v65, v66 offset0:32 offset1:36
	v_mul_f32_e32 v65, v58, v64
	v_mul_f32_e32 v66, v59, v64
	ds_write2st64_b32 v160, v65, v66 offset0:40 offset1:44
	v_mul_f32_e32 v65, v60, v64
	v_mul_f32_e32 v66, v61, v64
	ds_write2st64_b32 v160, v65, v66 offset0:48 offset1:52
	v_mul_f32_e32 v65, v62, v64
	v_mul_f32_e32 v66, v63, v64
	ds_write2st64_b32 v160, v65, v66 offset0:56 offset1:60
	v_mul_f32_e32 v65, v32, v64
	v_mul_f32_e32 v66, v33, v64
	ds_write2st64_b32 v160, v65, v66 offset0:64 offset1:68
	v_mul_f32_e32 v65, v34, v64
	v_mul_f32_e32 v66, v35, v64
	ds_write2st64_b32 v160, v65, v66 offset0:72 offset1:76
	v_mul_f32_e32 v65, v36, v64
	v_mul_f32_e32 v66, v37, v64
	ds_write2st64_b32 v160, v65, v66 offset0:80 offset1:84
	v_mul_f32_e32 v65, v38, v64
	v_mul_f32_e32 v66, v39, v64
	ds_write2st64_b32 v160, v65, v66 offset0:88 offset1:92
	v_mul_f32_e32 v65, v40, v64
	v_mul_f32_e32 v66, v41, v64
	ds_write2st64_b32 v160, v65, v66 offset0:96 offset1:100
	v_mul_f32_e32 v65, v42, v64
	v_mul_f32_e32 v66, v43, v64
	ds_write2st64_b32 v160, v65, v66 offset0:104 offset1:108
	v_mul_f32_e32 v65, v44, v64
	v_mul_f32_e32 v66, v45, v64
	ds_write2st64_b32 v160, v65, v66 offset0:112 offset1:116
	v_mul_f32_e32 v65, v46, v64
	v_mul_f32_e32 v66, v47, v64
	ds_write2st64_b32 v160, v65, v66 offset0:120 offset1:124
	v_mul_f32_e32 v65, v16, v64
	v_mul_f32_e32 v66, v17, v64
	ds_write2st64_b32 v160, v65, v66 offset0:128 offset1:132
	v_mul_f32_e32 v65, v18, v64
	v_mul_f32_e32 v66, v19, v64
	ds_write2st64_b32 v160, v65, v66 offset0:136 offset1:140
	v_mul_f32_e32 v65, v20, v64
	v_mul_f32_e32 v66, v21, v64
	ds_write2st64_b32 v160, v65, v66 offset0:144 offset1:148
	v_mul_f32_e32 v65, v22, v64
	v_mul_f32_e32 v66, v23, v64
	ds_write2st64_b32 v160, v65, v66 offset0:152 offset1:156
	v_mul_f32_e32 v65, v24, v64
	v_mul_f32_e32 v66, v25, v64
	ds_write2st64_b32 v160, v65, v66 offset0:160 offset1:164
	v_mul_f32_e32 v65, v26, v64
	v_mul_f32_e32 v66, v27, v64
	ds_write2st64_b32 v160, v65, v66 offset0:168 offset1:172
	v_mul_f32_e32 v65, v28, v64
	v_mul_f32_e32 v66, v29, v64
	ds_write2st64_b32 v160, v65, v66 offset0:176 offset1:180
	v_mul_f32_e32 v65, v30, v64
	v_mul_f32_e32 v66, v31, v64
	ds_write2st64_b32 v160, v65, v66 offset0:184 offset1:188
	v_mul_f32_e32 v65, v0, v64
	v_mul_f32_e32 v66, v1, v64
	ds_write2st64_b32 v160, v65, v66 offset0:192 offset1:196
	v_mul_f32_e32 v65, v2, v64
	v_mul_f32_e32 v66, v3, v64
	ds_write2st64_b32 v160, v65, v66 offset0:200 offset1:204
	v_mul_f32_e32 v65, v4, v64
	v_mul_f32_e32 v66, v5, v64
	ds_write2st64_b32 v160, v65, v66 offset0:208 offset1:212
	v_mul_f32_e32 v65, v6, v64
	v_mul_f32_e32 v66, v7, v64
	ds_write2st64_b32 v160, v65, v66 offset0:216 offset1:220
	v_mul_f32_e32 v65, v8, v64
	v_mul_f32_e32 v66, v9, v64
	ds_write2st64_b32 v160, v65, v66 offset0:224 offset1:228
	v_mul_f32_e32 v65, v10, v64
	v_mul_f32_e32 v66, v11, v64
	ds_write2st64_b32 v160, v65, v66 offset0:232 offset1:236
	v_mul_f32_e32 v65, v12, v64
	v_mul_f32_e32 v66, v13, v64
	ds_write2st64_b32 v160, v65, v66 offset0:240 offset1:244
	v_mul_f32_e32 v65, v14, v64
	v_mul_f32_e32 v66, v15, v64
	ds_write2st64_b32 v160, v65, v66 offset0:248 offset1:252
